# grid barrier: XCD leader releases its own XCD with a plain store of the new generation (stays in that XCD's L2) instead of an atomic add
# speedup vs baseline: 1.0061x; 1.0061x over previous
.LBB0_1114:
	s_or_b64 exec, exec, s[8:9]
	v_cvt_f32_u32_e32 v5, v3
	s_waitcnt vmcnt(0)
	v_readfirstlane_b32 s8, v4
	v_sub_u32_e32 v4, 0, v3
	v_rcp_iflag_f32_e32 v5, v5
	v_add_u32_e32 v6, s8, v0
	v_mul_f32_e32 v5, 0x4f7ffffe, v5
	v_cvt_u32_f32_e32 v5, v5
	v_mul_lo_u32 v0, v4, v5
	v_mul_hi_u32 v0, v5, v0
	v_add_u32_e32 v0, v5, v0
	v_mul_hi_u32 v0, v6, v0
	v_mul_lo_u32 v4, v0, v3
	v_sub_u32_e32 v4, v6, v4
	v_add_u32_e32 v5, 1, v0
	v_cmp_ge_u32_e32 vcc, v4, v3
	s_nop 1
	v_cndmask_b32_e32 v0, v0, v5, vcc
	v_sub_u32_e32 v5, v4, v3
	v_cndmask_b32_e32 v4, v4, v5, vcc
	v_add_u32_e32 v5, 1, v0
	v_cmp_ge_u32_e32 vcc, v4, v3
	v_add_u32_e32 v4, 1, v6
	s_nop 0
	v_cndmask_b32_e32 v0, v0, v5, vcc
	v_add_u32_e32 v7, 1, v0
	v_mul_lo_u32 v5, v3, v0
	v_add_u32_e32 v3, v5, v3
	v_cmp_ne_u32_e32 vcc, v4, v3
	s_and_saveexec_b64 s[8:9], vcc
	s_xor_b64 s[8:9], exec, s[8:9]
	s_cbranch_execz .LBB0_1128
	v_readlane_b32 s10, v253, 28
	v_readlane_b32 s11, v253, 29
	s_waitcnt lgkmcnt(0)
	s_nop 3
	buffer_inv sc1
	global_load_dword v2, v1, s[10:11] sc1
	s_waitcnt vmcnt(0)
	v_cmp_eq_u32_e32 vcc, v2, v0
	s_and_saveexec_b64 s[10:11], vcc
	s_cbranch_execz .LBB0_1127
	s_mov_b32 s24, 1
	s_mov_b64 s[12:13], 0
	s_branch .LBB0_1118

.LBB0_1145:
	s_or_b64 exec, exec, s[8:9]
	s_mov_b64 s[8:9], exec
	v_mbcnt_lo_u32_b32 v0, s8, 0
	v_mbcnt_hi_u32_b32 v0, s9, v0
	v_cmp_eq_u32_e32 vcc, 0, v0
	s_waitcnt vmcnt(0)
	s_and_saveexec_b64 s[10:11], vcc
	s_cbranch_execz .LBB0_1147
	s_bcnt1_i32_b64 s8, s[8:9]
	v_mov_b32_e32 v0, s8
	v_readlane_b32 s8, v253, 28
	v_readlane_b32 s9, v253, 29
	s_nop 4
	global_store_dword v1, v7, s[8:9]
